# Q and KV GEMM epilogues: the eight per-row-group ssq loads issued together at the top
# speedup vs baseline: 1.0002x; 1.0002x over previous
.LBB0_475:
	v_lshl_add_u32 v146, s40, 8, v153
	v_ashrrev_i32_e32 v147, 31, v146
	v_lshl_add_u64 v[148:149], v[146:147], 2, s[92:93]
	global_load_dword v150, v[148:149], off
	global_load_dword v182, v[148:149], off offset:64
	global_load_dword v183, v[148:149], off offset:128
	global_load_dword v184, v[148:149], off offset:192
	global_load_dword v185, v[148:149], off offset:512
	global_load_dword v186, v[148:149], off offset:576
	global_load_dword v187, v[148:149], off offset:640
	global_load_dword v188, v[148:149], off offset:704
	s_lshl_b32 s19, s24, 8
	s_or_b32 s24, s19, s51
	s_mul_hi_i32 s19, s24, 0x2aaaaaab
	s_lshr_b32 s25, s19, 31
	s_lshr_b32 s19, s19, 5
	s_add_i32 s19, s19, s25
	s_mulk_i32 s19, 0xc0
	s_sub_i32 s19, s24, s19
	s_cmpk_gt_i32 s19, 0x7f
	v_bfe_u32 v147, v146, 6, 5
	s_cselect_b64 s[26:27], -1, 0
	s_cmpk_lt_i32 s19, 0x80
	s_waitcnt vmcnt(0)
	v_fmamk_f32 v150, v150, 0x3b000000, v165
	v_rsq_f32_e32 v150, v150
	s_nop 0
	v_pk_mul_f32 v[126:127], v[126:127], v[150:151] op_sel_hi:[1,0]
	v_pk_mul_f32 v[124:125], v[124:125], v[150:151] op_sel_hi:[1,0]
	v_pk_mul_f32 v[122:123], v[122:123], v[150:151] op_sel_hi:[1,0]
	v_pk_mul_f32 v[120:121], v[120:121], v[150:151] op_sel_hi:[1,0]
	s_cbranch_scc1 .LBB0_477
	s_cmpk_lt_u32 s19, 0xa0
	s_cselect_b64 vcc, -1, 0
	v_cndmask_b32_e32 v151, v152, v147, vcc
	v_cvt_f32_ubyte0_e32 v151, v151
	v_mul_f32_e32 v166, v155, v151
	v_mul_f32_e32 v167, 0.15915494, v166
	v_cos_f32_e32 v166, v167
	v_sin_f32_e32 v168, v167
	v_mul_f32_e32 v167, v156, v151
	v_mul_f32_e32 v169, 0.15915494, v167
	v_mul_f32_e32 v170, v157, v151
	v_mul_f32_e32 v151, v158, v151
	v_cos_f32_e32 v167, v169
	v_sin_f32_e32 v169, v169
	v_mul_f32_e32 v170, 0.15915494, v170
	v_mul_f32_e32 v151, 0.15915494, v151
	v_cos_f32_e32 v173, v170
	v_sin_f32_e32 v175, v170
	v_cos_f32_e32 v176, v151
	v_sin_f32_e32 v177, v151
	v_pk_mul_f32 v[170:171], v[168:169], v[120:121]
	v_pk_mul_f32 v[120:121], v[166:167], v[120:121]
	v_mul_f32_e32 v174, v175, v122
	v_mul_f32_e32 v178, v173, v122
	v_mov_b32_e32 v122, v127
	v_pk_fma_f32 v[166:167], v[166:167], v[124:125], v[170:171] neg_lo:[0,0,1] neg_hi:[0,0,1]
	v_mov_b32_e32 v170, v177
	v_mov_b32_e32 v171, v176
	v_mul_f32_e32 v172, v173, v126
	v_mul_f32_e32 v180, v175, v126
	v_pk_mul_f32 v[126:127], v[176:177], v[122:123]
	v_pk_mul_f32 v[122:123], v[170:171], v[122:123]
	v_mov_b32_e32 v173, v126
	v_mov_b32_e32 v175, v127
	v_mov_b32_e32 v181, v122
	v_mov_b32_e32 v179, v123
	v_pk_add_f32 v[126:127], v[172:173], v[174:175] neg_lo:[0,1] neg_hi:[0,1]
	v_pk_fma_f32 v[120:121], v[168:169], v[124:125], v[120:121]
	v_pk_add_f32 v[122:123], v[180:181], v[178:179]
	v_mov_b32_e32 v124, v166
	v_mov_b32_e32 v125, v167

.LBB0_479:
	v_cvt_pk_bf16_f32 v116, v116, v117
	v_cvt_pk_bf16_f32 v117, v118, v119
	v_cvt_pk_bf16_f32 v118, v112, v113
	v_cvt_pk_bf16_f32 v119, v114, v115
	global_store_dwordx4 v[120:121], v[116:119], off offset:256
	s_nop 1
	v_mov_b32_e32 v112, v182
	v_cndmask_b32_e64 v113, 0, 1, s[26:27]
	v_cmp_ne_u32_e64 s[38:39], 1, v113
	s_andn2_b64 vcc, exec, s[26:27]
	s_waitcnt vmcnt(0)
	v_fmamk_f32 v112, v112, 0x3b000000, v165
	v_rsq_f32_e32 v112, v112
	s_nop 0
	v_pk_mul_f32 v[110:111], v[110:111], v[112:113] op_sel_hi:[1,0]
	v_pk_mul_f32 v[108:109], v[108:109], v[112:113] op_sel_hi:[1,0]
	v_pk_mul_f32 v[106:107], v[106:107], v[112:113] op_sel_hi:[1,0]
	v_pk_mul_f32 v[104:105], v[104:105], v[112:113] op_sel_hi:[1,0]
	s_cbranch_vccnz .LBB0_481
	s_cmpk_lt_u32 s19, 0xa0
	s_cselect_b64 vcc, -1, 0
	v_cndmask_b32_e32 v113, v159, v147, vcc
	v_cvt_f32_ubyte0_e32 v113, v113
	v_mul_f32_e32 v114, v155, v113
	v_mul_f32_e32 v115, 0.15915494, v114
	v_cos_f32_e32 v114, v115
	v_sin_f32_e32 v116, v115
	v_mul_f32_e32 v115, v156, v113
	v_mul_f32_e32 v117, 0.15915494, v115
	v_mul_f32_e32 v118, v157, v113
	v_mul_f32_e32 v113, v158, v113
	v_cos_f32_e32 v115, v117
	v_sin_f32_e32 v117, v117
	v_mul_f32_e32 v118, 0.15915494, v118
	v_mul_f32_e32 v113, 0.15915494, v113
	v_cos_f32_e32 v121, v118
	v_sin_f32_e32 v123, v118
	v_cos_f32_e32 v124, v113
	v_sin_f32_e32 v125, v113
	v_pk_mul_f32 v[118:119], v[116:117], v[104:105]
	v_pk_mul_f32 v[104:105], v[114:115], v[104:105]
	v_mul_f32_e32 v122, v123, v106
	v_mul_f32_e32 v126, v121, v106
	v_mov_b32_e32 v106, v111
	v_pk_fma_f32 v[114:115], v[114:115], v[108:109], v[118:119] neg_lo:[0,0,1] neg_hi:[0,0,1]
	v_mov_b32_e32 v118, v125
	v_mov_b32_e32 v119, v124
	v_mul_f32_e32 v120, v121, v110
	v_mul_f32_e32 v150, v123, v110
	v_pk_mul_f32 v[110:111], v[124:125], v[106:107]
	v_pk_mul_f32 v[106:107], v[118:119], v[106:107]
	v_mov_b32_e32 v121, v110
	v_mov_b32_e32 v123, v111
	v_mov_b32_e32 v151, v106
	v_mov_b32_e32 v127, v107
	v_pk_add_f32 v[110:111], v[120:121], v[122:123] neg_lo:[0,1] neg_hi:[0,1]
	v_pk_fma_f32 v[104:105], v[116:117], v[108:109], v[104:105]
	v_pk_add_f32 v[106:107], v[150:151], v[126:127]
	v_mov_b32_e32 v108, v114
	v_mov_b32_e32 v109, v115

.LBB0_483:
	v_cvt_pk_bf16_f32 v100, v100, v101
	v_cvt_pk_bf16_f32 v101, v102, v103
	v_cvt_pk_bf16_f32 v102, v96, v97
	v_cvt_pk_bf16_f32 v103, v98, v99
	global_store_dwordx4 v[104:105], v[100:103], off offset:256
	s_nop 1
	v_mov_b32_e32 v96, v183
	s_and_b64 vcc, exec, s[38:39]
	s_waitcnt vmcnt(0)
	v_fmamk_f32 v96, v96, 0x3b000000, v165
	v_rsq_f32_e32 v96, v96
	s_nop 0
	v_pk_mul_f32 v[94:95], v[94:95], v[96:97] op_sel_hi:[1,0]
	v_pk_mul_f32 v[92:93], v[92:93], v[96:97] op_sel_hi:[1,0]
	v_pk_mul_f32 v[90:91], v[90:91], v[96:97] op_sel_hi:[1,0]
	v_pk_mul_f32 v[88:89], v[88:89], v[96:97] op_sel_hi:[1,0]
	s_cbranch_vccnz .LBB0_485
	s_cmpk_lt_u32 s19, 0xa0
	s_cselect_b64 vcc, -1, 0
	v_cndmask_b32_e32 v97, v160, v147, vcc
	v_cvt_f32_ubyte0_e32 v97, v97
	v_mul_f32_e32 v98, v155, v97
	v_mul_f32_e32 v99, 0.15915494, v98
	v_cos_f32_e32 v98, v99
	v_sin_f32_e32 v100, v99
	v_mul_f32_e32 v99, v156, v97
	v_mul_f32_e32 v101, 0.15915494, v99
	v_mul_f32_e32 v102, v157, v97
	v_mul_f32_e32 v97, v158, v97
	v_cos_f32_e32 v99, v101
	v_sin_f32_e32 v101, v101
	v_mul_f32_e32 v102, 0.15915494, v102
	v_mul_f32_e32 v97, 0.15915494, v97
	v_cos_f32_e32 v105, v102
	v_sin_f32_e32 v107, v102
	v_cos_f32_e32 v108, v97
	v_sin_f32_e32 v109, v97
	v_pk_mul_f32 v[102:103], v[100:101], v[88:89]
	v_pk_mul_f32 v[88:89], v[98:99], v[88:89]
	v_mul_f32_e32 v106, v107, v90
	v_mul_f32_e32 v110, v105, v90
	v_mov_b32_e32 v90, v95
	v_pk_fma_f32 v[98:99], v[98:99], v[92:93], v[102:103] neg_lo:[0,0,1] neg_hi:[0,0,1]
	v_mov_b32_e32 v102, v109
	v_mov_b32_e32 v103, v108
	v_mul_f32_e32 v104, v105, v94
	v_mul_f32_e32 v112, v107, v94
	v_pk_mul_f32 v[94:95], v[108:109], v[90:91]
	v_pk_mul_f32 v[90:91], v[102:103], v[90:91]
	v_mov_b32_e32 v105, v94
	v_mov_b32_e32 v107, v95
	v_mov_b32_e32 v113, v90
	v_mov_b32_e32 v111, v91
	v_pk_add_f32 v[94:95], v[104:105], v[106:107] neg_lo:[0,1] neg_hi:[0,1]
	v_pk_fma_f32 v[88:89], v[100:101], v[92:93], v[88:89]
	v_pk_add_f32 v[90:91], v[112:113], v[110:111]
	v_mov_b32_e32 v92, v98
	v_mov_b32_e32 v93, v99

.LBB0_487:
	v_cvt_pk_bf16_f32 v84, v84, v85
	v_cvt_pk_bf16_f32 v85, v86, v87
	v_cvt_pk_bf16_f32 v86, v80, v81
	v_cvt_pk_bf16_f32 v87, v82, v83
	global_store_dwordx4 v[88:89], v[84:87], off offset:256
	s_nop 1
	v_mov_b32_e32 v80, v184
	s_and_b64 vcc, exec, s[38:39]
	s_waitcnt vmcnt(0)
	v_fmamk_f32 v80, v80, 0x3b000000, v165
	v_rsq_f32_e32 v80, v80
	s_nop 0
	v_pk_mul_f32 v[78:79], v[78:79], v[80:81] op_sel_hi:[1,0]
	v_pk_mul_f32 v[76:77], v[76:77], v[80:81] op_sel_hi:[1,0]
	v_pk_mul_f32 v[74:75], v[74:75], v[80:81] op_sel_hi:[1,0]
	v_pk_mul_f32 v[72:73], v[72:73], v[80:81] op_sel_hi:[1,0]
	s_cbranch_vccnz .LBB0_489
	s_cmpk_lt_u32 s19, 0xa0
	s_cselect_b64 vcc, -1, 0
	v_cndmask_b32_e32 v81, v161, v147, vcc
	v_cvt_f32_ubyte0_e32 v81, v81
	v_mul_f32_e32 v82, v155, v81
	v_mul_f32_e32 v83, 0.15915494, v82
	v_cos_f32_e32 v82, v83
	v_sin_f32_e32 v84, v83
	v_mul_f32_e32 v83, v156, v81
	v_mul_f32_e32 v85, 0.15915494, v83
	v_mul_f32_e32 v86, v157, v81
	v_mul_f32_e32 v81, v158, v81
	v_cos_f32_e32 v83, v85
	v_sin_f32_e32 v85, v85
	v_mul_f32_e32 v86, 0.15915494, v86
	v_mul_f32_e32 v81, 0.15915494, v81
	v_cos_f32_e32 v89, v86
	v_sin_f32_e32 v91, v86
	v_cos_f32_e32 v92, v81
	v_sin_f32_e32 v93, v81
	v_pk_mul_f32 v[86:87], v[84:85], v[72:73]
	v_pk_mul_f32 v[72:73], v[82:83], v[72:73]
	v_mul_f32_e32 v90, v91, v74
	v_mul_f32_e32 v94, v89, v74
	v_mov_b32_e32 v74, v79
	v_pk_fma_f32 v[82:83], v[82:83], v[76:77], v[86:87] neg_lo:[0,0,1] neg_hi:[0,0,1]
	v_mov_b32_e32 v86, v93
	v_mov_b32_e32 v87, v92
	v_mul_f32_e32 v88, v89, v78
	v_mul_f32_e32 v96, v91, v78
	v_pk_mul_f32 v[78:79], v[92:93], v[74:75]
	v_pk_mul_f32 v[74:75], v[86:87], v[74:75]
	v_mov_b32_e32 v89, v78
	v_mov_b32_e32 v91, v79
	v_mov_b32_e32 v97, v74
	v_mov_b32_e32 v95, v75
	v_pk_add_f32 v[78:79], v[88:89], v[90:91] neg_lo:[0,1] neg_hi:[0,1]
	v_pk_fma_f32 v[72:73], v[84:85], v[76:77], v[72:73]
	v_pk_add_f32 v[74:75], v[96:97], v[94:95]
	v_mov_b32_e32 v76, v82
	v_mov_b32_e32 v77, v83

.LBB0_491:
	v_cvt_pk_bf16_f32 v68, v68, v69
	v_cvt_pk_bf16_f32 v69, v70, v71
	v_cvt_pk_bf16_f32 v70, v64, v65
	v_cvt_pk_bf16_f32 v71, v66, v67
	global_store_dwordx4 v[72:73], v[68:71], off offset:256
	s_nop 1
	v_mov_b32_e32 v64, v185
	v_add_u32_e32 v67, 0x80, v146
	s_and_b64 vcc, exec, s[38:39]
	v_bfe_u32 v66, v67, 6, 5
	s_waitcnt vmcnt(0)
	v_fmamk_f32 v64, v64, 0x3b000000, v165
	v_rsq_f32_e32 v64, v64
	s_nop 0
	v_pk_mul_f32 v[62:63], v[62:63], v[64:65] op_sel_hi:[1,0]
	v_pk_mul_f32 v[60:61], v[60:61], v[64:65] op_sel_hi:[1,0]
	v_pk_mul_f32 v[58:59], v[58:59], v[64:65] op_sel_hi:[1,0]
	v_pk_mul_f32 v[56:57], v[56:57], v[64:65] op_sel_hi:[1,0]
	s_cbranch_vccnz .LBB0_493
	s_cmpk_lt_u32 s19, 0xa0
	s_cselect_b64 vcc, -1, 0
	v_cndmask_b32_e32 v65, v152, v66, vcc
	v_cvt_f32_ubyte0_e32 v65, v65
	v_mul_f32_e32 v68, v155, v65
	v_mul_f32_e32 v69, 0.15915494, v68
	v_cos_f32_e32 v68, v69
	v_sin_f32_e32 v70, v69
	v_mul_f32_e32 v69, v156, v65
	v_mul_f32_e32 v71, 0.15915494, v69
	v_mul_f32_e32 v72, v157, v65
	v_mul_f32_e32 v65, v158, v65
	v_cos_f32_e32 v69, v71
	v_sin_f32_e32 v71, v71
	v_mul_f32_e32 v72, 0.15915494, v72
	v_mul_f32_e32 v65, 0.15915494, v65
	v_cos_f32_e32 v75, v72
	v_sin_f32_e32 v77, v72
	v_cos_f32_e32 v78, v65
	v_sin_f32_e32 v79, v65
	v_pk_mul_f32 v[72:73], v[70:71], v[56:57]
	v_pk_mul_f32 v[56:57], v[68:69], v[56:57]
	v_mul_f32_e32 v76, v77, v58
	v_mul_f32_e32 v80, v75, v58
	v_mov_b32_e32 v58, v63
	v_pk_fma_f32 v[68:69], v[68:69], v[60:61], v[72:73] neg_lo:[0,0,1] neg_hi:[0,0,1]
	v_mov_b32_e32 v72, v79
	v_mov_b32_e32 v73, v78
	v_mul_f32_e32 v74, v75, v62
	v_mul_f32_e32 v82, v77, v62
	v_pk_mul_f32 v[62:63], v[78:79], v[58:59]
	v_pk_mul_f32 v[58:59], v[72:73], v[58:59]
	v_mov_b32_e32 v75, v62
	v_mov_b32_e32 v77, v63
	v_mov_b32_e32 v83, v58
	v_mov_b32_e32 v81, v59
	v_pk_add_f32 v[62:63], v[74:75], v[76:77] neg_lo:[0,1] neg_hi:[0,1]
	v_pk_fma_f32 v[56:57], v[70:71], v[60:61], v[56:57]
	v_pk_add_f32 v[58:59], v[82:83], v[80:81]
	v_mov_b32_e32 v60, v68
	v_mov_b32_e32 v61, v69

.LBB0_495:
	v_cvt_pk_bf16_f32 v52, v52, v53
	v_cvt_pk_bf16_f32 v53, v54, v55
	v_cvt_pk_bf16_f32 v54, v48, v49
	v_cvt_pk_bf16_f32 v55, v50, v51
	global_store_dwordx4 v[56:57], v[52:55], off offset:256
	s_nop 1
	v_mov_b32_e32 v48, v186
	s_and_b64 vcc, exec, s[38:39]
	s_waitcnt vmcnt(0)
	v_fmamk_f32 v48, v48, 0x3b000000, v165
	v_rsq_f32_e32 v48, v48
	s_nop 0
	v_pk_mul_f32 v[46:47], v[46:47], v[48:49] op_sel_hi:[1,0]
	v_pk_mul_f32 v[44:45], v[44:45], v[48:49] op_sel_hi:[1,0]
	v_pk_mul_f32 v[42:43], v[42:43], v[48:49] op_sel_hi:[1,0]
	v_pk_mul_f32 v[40:41], v[40:41], v[48:49] op_sel_hi:[1,0]
	s_cbranch_vccnz .LBB0_497
	s_cmpk_lt_u32 s19, 0xa0
	s_cselect_b64 vcc, -1, 0
	v_cndmask_b32_e32 v49, v159, v66, vcc
	v_cvt_f32_ubyte0_e32 v49, v49
	v_mul_f32_e32 v50, v155, v49
	v_mul_f32_e32 v51, 0.15915494, v50
	v_cos_f32_e32 v50, v51
	v_sin_f32_e32 v52, v51
	v_mul_f32_e32 v51, v156, v49
	v_mul_f32_e32 v53, 0.15915494, v51
	v_mul_f32_e32 v54, v157, v49
	v_mul_f32_e32 v49, v158, v49
	v_cos_f32_e32 v51, v53
	v_sin_f32_e32 v53, v53
	v_mul_f32_e32 v54, 0.15915494, v54
	v_mul_f32_e32 v49, 0.15915494, v49
	v_cos_f32_e32 v57, v54
	v_sin_f32_e32 v59, v54
	v_cos_f32_e32 v60, v49
	v_sin_f32_e32 v61, v49
	v_pk_mul_f32 v[54:55], v[52:53], v[40:41]
	v_pk_mul_f32 v[40:41], v[50:51], v[40:41]
	v_mul_f32_e32 v58, v59, v42
	v_mul_f32_e32 v62, v57, v42
	v_mov_b32_e32 v42, v47
	v_pk_fma_f32 v[50:51], v[50:51], v[44:45], v[54:55] neg_lo:[0,0,1] neg_hi:[0,0,1]
	v_mov_b32_e32 v54, v61
	v_mov_b32_e32 v55, v60
	v_mul_f32_e32 v56, v57, v46
	v_mul_f32_e32 v64, v59, v46
	v_pk_mul_f32 v[46:47], v[60:61], v[42:43]
	v_pk_mul_f32 v[42:43], v[54:55], v[42:43]
	v_mov_b32_e32 v57, v46
	v_mov_b32_e32 v59, v47
	v_mov_b32_e32 v65, v42
	v_mov_b32_e32 v63, v43
	v_pk_add_f32 v[46:47], v[56:57], v[58:59] neg_lo:[0,1] neg_hi:[0,1]
	v_pk_fma_f32 v[40:41], v[52:53], v[44:45], v[40:41]
	v_pk_add_f32 v[42:43], v[64:65], v[62:63]
	v_mov_b32_e32 v44, v50
	v_mov_b32_e32 v45, v51

.LBB0_499:
	v_cvt_pk_bf16_f32 v36, v36, v37
	v_cvt_pk_bf16_f32 v37, v38, v39
	v_cvt_pk_bf16_f32 v38, v32, v33
	v_cvt_pk_bf16_f32 v39, v34, v35
	global_store_dwordx4 v[40:41], v[36:39], off offset:256
	s_nop 1
	v_mov_b32_e32 v32, v187
	s_and_b64 vcc, exec, s[38:39]
	s_waitcnt vmcnt(0)
	v_fmamk_f32 v32, v32, 0x3b000000, v165
	v_rsq_f32_e32 v32, v32
	s_nop 0
	v_pk_mul_f32 v[30:31], v[30:31], v[32:33] op_sel_hi:[1,0]
	v_pk_mul_f32 v[28:29], v[28:29], v[32:33] op_sel_hi:[1,0]
	v_pk_mul_f32 v[26:27], v[26:27], v[32:33] op_sel_hi:[1,0]
	v_pk_mul_f32 v[24:25], v[24:25], v[32:33] op_sel_hi:[1,0]
	s_cbranch_vccnz .LBB0_501
	s_cmpk_lt_u32 s19, 0xa0
	s_cselect_b64 vcc, -1, 0
	v_cndmask_b32_e32 v33, v160, v66, vcc
	v_cvt_f32_ubyte0_e32 v33, v33
	v_mul_f32_e32 v34, v155, v33
	v_mul_f32_e32 v35, 0.15915494, v34
	v_cos_f32_e32 v34, v35
	v_sin_f32_e32 v36, v35
	v_mul_f32_e32 v35, v156, v33
	v_mul_f32_e32 v37, 0.15915494, v35
	v_mul_f32_e32 v38, v157, v33
	v_mul_f32_e32 v33, v158, v33
	v_cos_f32_e32 v35, v37
	v_sin_f32_e32 v37, v37
	v_mul_f32_e32 v38, 0.15915494, v38
	v_mul_f32_e32 v33, 0.15915494, v33
	v_cos_f32_e32 v41, v38
	v_sin_f32_e32 v43, v38
	v_cos_f32_e32 v44, v33
	v_sin_f32_e32 v45, v33
	v_pk_mul_f32 v[38:39], v[36:37], v[24:25]
	v_pk_mul_f32 v[24:25], v[34:35], v[24:25]
	v_mul_f32_e32 v42, v43, v26
	v_mul_f32_e32 v46, v41, v26
	v_mov_b32_e32 v26, v31
	v_pk_fma_f32 v[34:35], v[34:35], v[28:29], v[38:39] neg_lo:[0,0,1] neg_hi:[0,0,1]
	v_mov_b32_e32 v38, v45
	v_mov_b32_e32 v39, v44
	v_mul_f32_e32 v40, v41, v30
	v_mul_f32_e32 v48, v43, v30
	v_pk_mul_f32 v[30:31], v[44:45], v[26:27]
	v_pk_mul_f32 v[26:27], v[38:39], v[26:27]
	v_mov_b32_e32 v41, v30
	v_mov_b32_e32 v43, v31
	v_mov_b32_e32 v49, v26
	v_mov_b32_e32 v47, v27
	v_pk_add_f32 v[30:31], v[40:41], v[42:43] neg_lo:[0,1] neg_hi:[0,1]
	v_pk_fma_f32 v[24:25], v[36:37], v[28:29], v[24:25]
	v_pk_add_f32 v[26:27], v[48:49], v[46:47]
	v_mov_b32_e32 v28, v34
	v_mov_b32_e32 v29, v35

.LBB0_503:
	v_cvt_pk_bf16_f32 v20, v20, v21
	v_cvt_pk_bf16_f32 v21, v22, v23
	v_cvt_pk_bf16_f32 v22, v16, v17
	v_cvt_pk_bf16_f32 v23, v18, v19
	global_store_dwordx4 v[24:25], v[20:23], off offset:256
	s_nop 1
	v_mov_b32_e32 v16, v188
	s_and_b64 vcc, exec, s[38:39]
	s_waitcnt vmcnt(0)
	v_fmamk_f32 v16, v16, 0x3b000000, v165
	v_rsq_f32_e32 v16, v16
	s_nop 0
	v_pk_mul_f32 v[14:15], v[14:15], v[16:17] op_sel_hi:[1,0]
	v_pk_mul_f32 v[12:13], v[12:13], v[16:17] op_sel_hi:[1,0]
	v_pk_mul_f32 v[10:11], v[10:11], v[16:17] op_sel_hi:[1,0]
	v_pk_mul_f32 v[8:9], v[8:9], v[16:17] op_sel_hi:[1,0]
	s_cbranch_vccnz .LBB0_505
	s_cmpk_lt_u32 s19, 0xa0
	s_cselect_b64 vcc, -1, 0
	v_cndmask_b32_e32 v17, v161, v66, vcc
	v_cvt_f32_ubyte0_e32 v17, v17
	v_mul_f32_e32 v18, v155, v17
	v_mul_f32_e32 v19, 0.15915494, v18
	v_cos_f32_e32 v18, v19
	v_sin_f32_e32 v20, v19
	v_mul_f32_e32 v19, v156, v17
	v_mul_f32_e32 v21, 0.15915494, v19
	v_mul_f32_e32 v22, v157, v17
	v_mul_f32_e32 v17, v158, v17
	v_cos_f32_e32 v19, v21
	v_sin_f32_e32 v21, v21
	v_mul_f32_e32 v22, 0.15915494, v22
	v_mul_f32_e32 v17, 0.15915494, v17
	v_cos_f32_e32 v25, v22
	v_sin_f32_e32 v27, v22
	v_cos_f32_e32 v28, v17
	v_sin_f32_e32 v29, v17
	v_pk_mul_f32 v[22:23], v[20:21], v[8:9]
	v_pk_mul_f32 v[8:9], v[18:19], v[8:9]
	v_mul_f32_e32 v26, v27, v10
	v_mul_f32_e32 v30, v25, v10
	v_mov_b32_e32 v10, v15
	v_pk_fma_f32 v[18:19], v[18:19], v[12:13], v[22:23] neg_lo:[0,0,1] neg_hi:[0,0,1]
	v_mov_b32_e32 v22, v29
	v_mov_b32_e32 v23, v28
	v_mul_f32_e32 v24, v25, v14
	v_mul_f32_e32 v32, v27, v14
	v_pk_mul_f32 v[14:15], v[28:29], v[10:11]
	v_pk_mul_f32 v[10:11], v[22:23], v[10:11]
	v_mov_b32_e32 v25, v14
	v_mov_b32_e32 v27, v15
	v_mov_b32_e32 v33, v10
	v_mov_b32_e32 v31, v11
	v_pk_add_f32 v[14:15], v[24:25], v[26:27] neg_lo:[0,1] neg_hi:[0,1]
	v_pk_fma_f32 v[8:9], v[20:21], v[12:13], v[8:9]
	v_pk_add_f32 v[10:11], v[32:33], v[30:31]
	v_mov_b32_e32 v12, v18
	v_mov_b32_e32 v13, v19

.LBB0_523:
	v_lshl_add_u32 v144, s69, 8, v146
	v_ashrrev_i32_e32 v145, 31, v144
	v_lshl_add_u64 v[142:143], v[144:145], 2, s[6:7]
	global_load_dword v152, v[142:143], off
	global_load_dword v156, v[142:143], off offset:64
	global_load_dword v157, v[142:143], off offset:128
	global_load_dword v158, v[142:143], off offset:192
	global_load_dword v159, v[142:143], off offset:512
	global_load_dword v160, v[142:143], off offset:576
	global_load_dword v161, v[142:143], off offset:640
	global_load_dword v162, v[142:143], off offset:704
	s_lshl_b32 s36, s70, 7
	s_ashr_i32 s37, s36, 31
	s_lshl_b64 s[36:37], s[36:37], 1
	s_mov_b64 s[38:39], 0x40000
	s_and_b64 vcc, exec, s[0:1]
	s_waitcnt vmcnt(0)
	v_fmamk_f32 v152, v152, 0x3b800000, v151
	v_rsq_f32_e32 v152, v152
	s_nop 0
	v_pk_mul_f32 v[112:113], v[112:113], v[152:153] op_sel_hi:[1,0]
	v_pk_mul_f32 v[154:155], v[114:115], v[152:153] op_sel_hi:[1,0]
	v_pk_mul_f32 v[118:119], v[118:119], v[152:153] op_sel_hi:[1,0]
	v_pk_mul_f32 v[116:117], v[116:117], v[152:153] op_sel_hi:[1,0]
	v_cvt_pk_bf16_f32 v114, v112, v113
	v_lshlrev_b64 v[112:113], 11, v[144:145]
	v_cvt_pk_bf16_f32 v116, v116, v117
	v_cvt_pk_bf16_f32 v117, v118, v119
	v_lshl_add_u64 v[118:119], s[18:19], 0, v[112:113]
	v_lshl_add_u64 v[118:119], v[118:119], 0, s[36:37]
	v_cvt_pk_bf16_f32 v115, v154, v155
	v_lshl_add_u64 v[118:119], v[118:119], 0, v[136:137]
	global_store_dwordx4 v[118:119], v[114:117], off
	v_pk_mul_f32 v[118:119], v[126:127], v[152:153] op_sel_hi:[1,0]
	s_nop 0
	v_pk_mul_f32 v[116:117], v[122:123], v[152:153] op_sel_hi:[1,0]
	v_pk_mul_f32 v[114:115], v[120:121], v[152:153] op_sel_hi:[1,0]
	v_pk_mul_f32 v[120:121], v[124:125], v[152:153] op_sel_hi:[1,0]
	v_cvt_pk_bf16_f32 v114, v114, v115
	v_cvt_pk_bf16_f32 v115, v116, v117
	v_cvt_pk_bf16_f32 v117, v118, v119
	v_lshl_add_u64 v[118:119], s[20:21], 0, v[112:113]
	v_lshl_add_u64 v[118:119], v[118:119], 0, s[36:37]
	v_cvt_pk_bf16_f32 v116, v120, v121
	v_lshl_add_u64 v[118:119], v[118:119], 0, v[136:137]
	global_store_dwordx4 v[118:119], v[114:117], off
	s_nop 1
	v_or_b32_e32 v114, 16, v144
	v_ashrrev_i32_e32 v115, 31, v114
	v_lshl_add_u64 v[116:117], v[114:115], 2, s[6:7]
	s_nop 1
	v_mov_b32_e32 v116, v156
	s_waitcnt vmcnt(0)
	v_fmamk_f32 v116, v116, 0x3b800000, v151
	v_rsq_f32_e32 v116, v116
	s_nop 0
	v_pk_mul_f32 v[98:99], v[98:99], v[116:117] op_sel_hi:[1,0]
	v_pk_mul_f32 v[96:97], v[96:97], v[116:117] op_sel_hi:[1,0]
	v_pk_mul_f32 v[100:101], v[100:101], v[116:117] op_sel_hi:[1,0]
	v_pk_mul_f32 v[102:103], v[102:103], v[116:117] op_sel_hi:[1,0]
	v_cvt_pk_bf16_f32 v96, v96, v97
	v_cvt_pk_bf16_f32 v97, v98, v99
	v_cvt_pk_bf16_f32 v98, v100, v101
	v_lshlrev_b64 v[100:101], 11, v[114:115]
	v_cvt_pk_bf16_f32 v99, v102, v103
	v_lshl_add_u64 v[102:103], s[18:19], 0, v[100:101]
	v_lshl_add_u64 v[102:103], v[102:103], 0, s[36:37]
	v_lshl_add_u64 v[102:103], v[102:103], 0, v[136:137]
	v_lshl_add_u64 v[100:101], s[20:21], 0, v[100:101]
	global_store_dwordx4 v[102:103], v[96:99], off
	v_pk_mul_f32 v[102:103], v[110:111], v[116:117] op_sel_hi:[1,0]
	v_lshl_add_u64 v[100:101], v[100:101], 0, s[36:37]
	v_pk_mul_f32 v[98:99], v[106:107], v[116:117] op_sel_hi:[1,0]
	v_pk_mul_f32 v[96:97], v[104:105], v[116:117] op_sel_hi:[1,0]
	v_pk_mul_f32 v[104:105], v[108:109], v[116:117] op_sel_hi:[1,0]
	v_cvt_pk_bf16_f32 v96, v96, v97
	v_cvt_pk_bf16_f32 v97, v98, v99
	v_cvt_pk_bf16_f32 v98, v104, v105
	v_cvt_pk_bf16_f32 v99, v102, v103
	v_lshl_add_u64 v[100:101], v[100:101], 0, v[136:137]
	global_store_dwordx4 v[100:101], v[96:99], off
	s_nop 1
	v_or_b32_e32 v96, 32, v144
	v_ashrrev_i32_e32 v97, 31, v96
	v_lshl_add_u64 v[98:99], v[96:97], 2, s[6:7]
	s_nop 1
	v_mov_b32_e32 v98, v157
	s_waitcnt vmcnt(0)
	v_fmamk_f32 v98, v98, 0x3b800000, v151
	v_rsq_f32_e32 v98, v98
	s_nop 0
	v_pk_mul_f32 v[82:83], v[82:83], v[98:99] op_sel_hi:[1,0]
	v_pk_mul_f32 v[80:81], v[80:81], v[98:99] op_sel_hi:[1,0]
	v_pk_mul_f32 v[84:85], v[84:85], v[98:99] op_sel_hi:[1,0]
	v_pk_mul_f32 v[86:87], v[86:87], v[98:99] op_sel_hi:[1,0]
	v_cvt_pk_bf16_f32 v80, v80, v81
	v_cvt_pk_bf16_f32 v81, v82, v83
	v_cvt_pk_bf16_f32 v82, v84, v85
	v_lshlrev_b64 v[84:85], 11, v[96:97]
	v_cvt_pk_bf16_f32 v83, v86, v87
	v_lshl_add_u64 v[86:87], s[18:19], 0, v[84:85]
	v_lshl_add_u64 v[86:87], v[86:87], 0, s[36:37]
	v_lshl_add_u64 v[86:87], v[86:87], 0, v[136:137]
	v_lshl_add_u64 v[84:85], s[20:21], 0, v[84:85]
	global_store_dwordx4 v[86:87], v[80:83], off
	v_pk_mul_f32 v[86:87], v[94:95], v[98:99] op_sel_hi:[1,0]
	v_lshl_add_u64 v[84:85], v[84:85], 0, s[36:37]
	v_pk_mul_f32 v[82:83], v[90:91], v[98:99] op_sel_hi:[1,0]
	v_pk_mul_f32 v[80:81], v[88:89], v[98:99] op_sel_hi:[1,0]
	v_pk_mul_f32 v[88:89], v[92:93], v[98:99] op_sel_hi:[1,0]
	v_cvt_pk_bf16_f32 v80, v80, v81
	v_cvt_pk_bf16_f32 v81, v82, v83
	v_cvt_pk_bf16_f32 v82, v88, v89
	v_cvt_pk_bf16_f32 v83, v86, v87
	v_lshl_add_u64 v[84:85], v[84:85], 0, v[136:137]
	global_store_dwordx4 v[84:85], v[80:83], off
	s_nop 1
	v_or_b32_e32 v80, 48, v144
	v_ashrrev_i32_e32 v81, 31, v80
	v_lshl_add_u64 v[82:83], v[80:81], 2, s[6:7]
	s_nop 1
	v_mov_b32_e32 v82, v158
	s_waitcnt vmcnt(0)
	v_fmamk_f32 v82, v82, 0x3b800000, v151
	v_rsq_f32_e32 v82, v82
	s_nop 0
	v_pk_mul_f32 v[74:75], v[74:75], v[82:83] op_sel_hi:[1,0]
	v_pk_mul_f32 v[72:73], v[72:73], v[82:83] op_sel_hi:[1,0]
	v_pk_mul_f32 v[76:77], v[76:77], v[82:83] op_sel_hi:[1,0]
	v_pk_mul_f32 v[78:79], v[78:79], v[82:83] op_sel_hi:[1,0]
	v_cvt_pk_bf16_f32 v72, v72, v73
	v_cvt_pk_bf16_f32 v73, v74, v75
	v_cvt_pk_bf16_f32 v74, v76, v77
	v_lshlrev_b64 v[76:77], 11, v[80:81]
	v_pk_mul_f32 v[66:67], v[66:67], v[82:83] op_sel_hi:[1,0]
	v_pk_mul_f32 v[64:65], v[64:65], v[82:83] op_sel_hi:[1,0]
	v_pk_mul_f32 v[68:69], v[68:69], v[82:83] op_sel_hi:[1,0]
	v_cvt_pk_bf16_f32 v75, v78, v79
	v_lshl_add_u64 v[78:79], s[18:19], 0, v[76:77]
	v_cvt_pk_bf16_f32 v64, v64, v65
	v_cvt_pk_bf16_f32 v65, v66, v67
	v_cvt_pk_bf16_f32 v66, v68, v69
	v_lshl_add_u64 v[68:69], s[20:21], 0, v[76:77]
	v_lshl_add_u64 v[78:79], v[78:79], 0, s[36:37]
	v_pk_mul_f32 v[70:71], v[70:71], v[82:83] op_sel_hi:[1,0]
	v_lshl_add_u64 v[68:69], v[68:69], 0, s[36:37]
	v_lshl_add_u64 v[78:79], v[78:79], 0, v[136:137]
	v_cvt_pk_bf16_f32 v67, v70, v71
	v_lshl_add_u64 v[68:69], v[68:69], 0, v[136:137]
	global_store_dwordx4 v[78:79], v[72:75], off
	global_store_dwordx4 v[68:69], v[64:67], off
	s_nop 1
	v_mov_b32_e32 v66, v159
	s_nop 0
	v_lshl_add_u64 v[64:65], v[112:113], 0, s[38:39]
	s_mov_b64 s[38:39], 0x48000
	s_waitcnt vmcnt(0)
	v_fmamk_f32 v66, v66, 0x3b800000, v151
	v_rsq_f32_e32 v66, v66
	s_nop 0
	v_pk_mul_f32 v[58:59], v[58:59], v[66:67] op_sel_hi:[1,0]
	v_pk_mul_f32 v[56:57], v[56:57], v[66:67] op_sel_hi:[1,0]
	v_pk_mul_f32 v[60:61], v[60:61], v[66:67] op_sel_hi:[1,0]
	v_pk_mul_f32 v[50:51], v[50:51], v[66:67] op_sel_hi:[1,0]
	v_pk_mul_f32 v[48:49], v[48:49], v[66:67] op_sel_hi:[1,0]
	v_pk_mul_f32 v[52:53], v[52:53], v[66:67] op_sel_hi:[1,0]
	v_cvt_pk_bf16_f32 v56, v56, v57
	v_cvt_pk_bf16_f32 v57, v58, v59
	v_cvt_pk_bf16_f32 v58, v60, v61
	v_lshl_add_u64 v[60:61], s[18:19], 0, v[64:65]
	v_cvt_pk_bf16_f32 v48, v48, v49
	v_cvt_pk_bf16_f32 v49, v50, v51
	v_cvt_pk_bf16_f32 v50, v52, v53
	v_lshl_add_u64 v[52:53], s[20:21], 0, v[64:65]
	v_pk_mul_f32 v[62:63], v[62:63], v[66:67] op_sel_hi:[1,0]
	v_lshl_add_u64 v[60:61], v[60:61], 0, s[36:37]
	v_pk_mul_f32 v[54:55], v[54:55], v[66:67] op_sel_hi:[1,0]
	v_lshl_add_u64 v[52:53], v[52:53], 0, s[36:37]
	v_cvt_pk_bf16_f32 v59, v62, v63
	v_lshl_add_u64 v[60:61], v[60:61], 0, v[136:137]
	v_cvt_pk_bf16_f32 v51, v54, v55
	v_lshl_add_u64 v[52:53], v[52:53], 0, v[136:137]
	global_store_dwordx4 v[60:61], v[56:59], off
	global_store_dwordx4 v[52:53], v[48:51], off
	s_nop 1
	v_mov_b32_e32 v50, v160
	s_nop 0
	v_lshl_add_u64 v[48:49], v[112:113], 0, s[38:39]
	s_mov_b64 s[38:39], 0x50000
	s_waitcnt vmcnt(0)
	v_fmamk_f32 v50, v50, 0x3b800000, v151
	v_rsq_f32_e32 v50, v50
	s_nop 0
	v_pk_mul_f32 v[42:43], v[42:43], v[50:51] op_sel_hi:[1,0]
	v_pk_mul_f32 v[40:41], v[40:41], v[50:51] op_sel_hi:[1,0]
	v_pk_mul_f32 v[44:45], v[44:45], v[50:51] op_sel_hi:[1,0]
	v_pk_mul_f32 v[34:35], v[34:35], v[50:51] op_sel_hi:[1,0]
	v_pk_mul_f32 v[32:33], v[32:33], v[50:51] op_sel_hi:[1,0]
	v_pk_mul_f32 v[36:37], v[36:37], v[50:51] op_sel_hi:[1,0]
	v_cvt_pk_bf16_f32 v40, v40, v41
	v_cvt_pk_bf16_f32 v41, v42, v43
	v_cvt_pk_bf16_f32 v42, v44, v45
	v_lshl_add_u64 v[44:45], s[18:19], 0, v[48:49]
	v_cvt_pk_bf16_f32 v32, v32, v33
	v_cvt_pk_bf16_f32 v33, v34, v35
	v_cvt_pk_bf16_f32 v34, v36, v37
	v_lshl_add_u64 v[36:37], s[20:21], 0, v[48:49]
	v_pk_mul_f32 v[46:47], v[46:47], v[50:51] op_sel_hi:[1,0]
	v_lshl_add_u64 v[44:45], v[44:45], 0, s[36:37]
	v_pk_mul_f32 v[38:39], v[38:39], v[50:51] op_sel_hi:[1,0]
	v_lshl_add_u64 v[36:37], v[36:37], 0, s[36:37]
	v_cvt_pk_bf16_f32 v43, v46, v47
	v_lshl_add_u64 v[44:45], v[44:45], 0, v[136:137]
	v_cvt_pk_bf16_f32 v35, v38, v39
	v_lshl_add_u64 v[36:37], v[36:37], 0, v[136:137]
	global_store_dwordx4 v[44:45], v[40:43], off
	global_store_dwordx4 v[36:37], v[32:35], off
	s_nop 1
	v_mov_b32_e32 v34, v161
	s_nop 0
	v_lshl_add_u64 v[32:33], v[112:113], 0, s[38:39]
	s_mov_b64 s[38:39], 0x58000
	s_waitcnt vmcnt(0)
	v_fmamk_f32 v34, v34, 0x3b800000, v151
	v_rsq_f32_e32 v34, v34
	s_nop 0
	v_pk_mul_f32 v[26:27], v[26:27], v[34:35] op_sel_hi:[1,0]
	v_pk_mul_f32 v[24:25], v[24:25], v[34:35] op_sel_hi:[1,0]
	v_pk_mul_f32 v[28:29], v[28:29], v[34:35] op_sel_hi:[1,0]
	v_pk_mul_f32 v[18:19], v[18:19], v[34:35] op_sel_hi:[1,0]
	v_pk_mul_f32 v[16:17], v[16:17], v[34:35] op_sel_hi:[1,0]
	v_pk_mul_f32 v[20:21], v[20:21], v[34:35] op_sel_hi:[1,0]
	v_cvt_pk_bf16_f32 v24, v24, v25
	v_cvt_pk_bf16_f32 v25, v26, v27
	v_cvt_pk_bf16_f32 v26, v28, v29
	v_lshl_add_u64 v[28:29], s[18:19], 0, v[32:33]
	v_cvt_pk_bf16_f32 v16, v16, v17
	v_cvt_pk_bf16_f32 v17, v18, v19
	v_cvt_pk_bf16_f32 v18, v20, v21
	v_lshl_add_u64 v[20:21], s[20:21], 0, v[32:33]
	v_pk_mul_f32 v[30:31], v[30:31], v[34:35] op_sel_hi:[1,0]
	v_lshl_add_u64 v[28:29], v[28:29], 0, s[36:37]
	v_pk_mul_f32 v[22:23], v[22:23], v[34:35] op_sel_hi:[1,0]
	v_lshl_add_u64 v[20:21], v[20:21], 0, s[36:37]
	v_cvt_pk_bf16_f32 v27, v30, v31
	v_lshl_add_u64 v[28:29], v[28:29], 0, v[136:137]
	v_cvt_pk_bf16_f32 v19, v22, v23
	v_lshl_add_u64 v[20:21], v[20:21], 0, v[136:137]
	global_store_dwordx4 v[28:29], v[24:27], off
	global_store_dwordx4 v[20:21], v[16:19], off
	s_nop 1
	v_mov_b32_e32 v18, v162
	s_nop 0
	v_lshl_add_u64 v[16:17], v[112:113], 0, s[38:39]
	s_waitcnt vmcnt(0)
	v_fmamk_f32 v18, v18, 0x3b800000, v151
	v_rsq_f32_e32 v18, v18
	s_nop 0
	v_pk_mul_f32 v[2:3], v[2:3], v[18:19] op_sel_hi:[1,0]
	v_pk_mul_f32 v[0:1], v[0:1], v[18:19] op_sel_hi:[1,0]
	v_pk_mul_f32 v[4:5], v[4:5], v[18:19] op_sel_hi:[1,0]
	v_cvt_pk_bf16_f32 v0, v0, v1
	v_cvt_pk_bf16_f32 v1, v2, v3
	v_cvt_pk_bf16_f32 v2, v4, v5
	v_lshl_add_u64 v[4:5], s[18:19], 0, v[16:17]
	v_pk_mul_f32 v[6:7], v[6:7], v[18:19] op_sel_hi:[1,0]
	v_lshl_add_u64 v[4:5], v[4:5], 0, s[36:37]
	v_cvt_pk_bf16_f32 v3, v6, v7
	v_lshl_add_u64 v[4:5], v[4:5], 0, v[136:137]
	global_store_dwordx4 v[4:5], v[0:3], off
	v_pk_mul_f32 v[4:5], v[14:15], v[18:19] op_sel_hi:[1,0]
	v_pk_mul_f32 v[6:7], v[12:13], v[18:19] op_sel_hi:[1,0]
	v_pk_mul_f32 v[2:3], v[10:11], v[18:19] op_sel_hi:[1,0]
	v_pk_mul_f32 v[0:1], v[8:9], v[18:19] op_sel_hi:[1,0]
	s_nop 0
	v_cvt_pk_bf16_f32 v0, v0, v1
	v_cvt_pk_bf16_f32 v1, v2, v3
	v_cvt_pk_bf16_f32 v3, v4, v5
	v_lshl_add_u64 v[4:5], s[20:21], 0, v[16:17]
	v_lshl_add_u64 v[4:5], v[4:5], 0, s[36:37]
	v_cvt_pk_bf16_f32 v2, v6, v7
	v_lshl_add_u64 v[4:5], v[4:5], 0, v[136:137]
	s_mov_b64 s[36:37], -1
	global_store_dwordx4 v[4:5], v[0:3], off
	s_cbranch_vccnz .LBB0_516
	s_andn2_b64 vcc, exec, s[4:5]
	s_cbranch_vccnz .LBB0_515
	s_barrier
	s_branch .LBB0_515
